# MoE down-projection GEMMs (phases 7 and 8): hipcc's fully unrolled 16-k-tile bodies replaced by a hand-written software-pipelined loop over all k-tiles (counted lgkmcnt waits, LDS-DMA predicated by ex
# baseline (speedup 1.0000x reference)
; DI void dma16(const void* src, void* lds_wave_base) { __builtin_amdgcn_global_load_lds((const unsigned*)src, (unsigned*)lds_wave_base, 16, 0, 0); }
; #define WAIT_V(n) asm volatile("s_waitcnt vmcnt(%0)" ::"n"(n) : "memory")
; #define RAW_BARRIER() do { asm volatile("s_waitcnt lgkmcnt(0)" ::: "memory"); __builtin_amdgcn_s_barrier(); } while (0)
; template <typename FA, typename FB, typename FE>
; DI void gemm_tile(char* lds, int K, int astride, int bstride, FA arow, FB brow, FE epi) {
;   const int tid = threadIdx.x, w = __builtin_amdgcn_readfirstlane(tid >> 6), lane = tid & 63, r = lane & 31, h8 = lane >> 5;
;   const int wm = w >> 1, wn = w & 1;
;   const bfr* ap[2]; const bfr* bp[2];
; #pragma unroll
;   for (int i = 0; i < 2; ++i) {
;     const int row = (w * 2 + i) * 16 + (lane >> 2);
;     const int sw = ((lane & 3) ^ ((row >> 2) & 3)) * 8;
;     ap[i] = arow(row) + sw;
;     bp[i] = brow(row) + sw;
;   }
;   int foff[2];
; #pragma unroll
;   for (int ks = 0; ks < 2; ++ks) foff[ks] = r * 64 + (((ks * 2 + h8) ^ ((r >> 2) & 3)) << 4);
;   f32x16 acc[2][4];
; #pragma unroll
;   for (int a = 0; a < 2; ++a)
; #pragma unroll
;     for (int b = 0; b < 4; ++b)
; #pragma unroll
;       for (int i = 0; i < 16; ++i) acc[a][b][i] = 0.f;
;   const int nk = K >> 5;
;   auto stage = [&](int buf, int kt) {
;     char* sa = lds + buf * 32768;
; #pragma unroll
;     for (int i = 0; i < 2; ++i) {
;       dma16(ap[i] + (size_t)kt * astride, sa + (w * 2 + i) * 1024);
;       dma16(bp[i] + (size_t)kt * bstride, sa + 16384 + (w * 2 + i) * 1024);
;     }
;   };
;   stage(0, 0); stage(1, 1); stage(2, 2);
;   for (int kt = 0; kt < nk; ++kt) {
;     if (kt + 2 < nk) WAIT_V(8); else if (kt + 1 < nk) WAIT_V(4); else WAIT_V(0);
;     RAW_BARRIER();
.LBB0_332:
	s_or_b64 exec, exec, s[6:7]
	s_mov_b32 s5, s53
	s_lshl_b64 s[6:7], s[4:5], 20
	s_lshl_b32 s4, s52, 2
	s_add_i32 s4, s4, 0x25e00
	v_mov_b32_e32 v2, s4
	s_waitcnt lgkmcnt(0)
	s_barrier
	ds_read_b32 v2, v2
	v_readfirstlane_b32 s8, v1
	s_lshr_b32 s9, s8, 6
	v_lshl_or_b32 v6, s9, 5, v145
	s_lshl_b32 s4, s65, 8
	s_waitcnt lgkmcnt(0)
	v_add_u32_e32 v7, v2, v173
	v_add_u32_e32 v4, v6, v7
	v_min_i32_e32 v4, 0x2ffff, v4
	v_ashrrev_i32_e32 v5, 31, v4
	v_lshlrev_b64 v[4:5], 6, v[4:5]
	v_lshl_add_u64 v[136:137], v[132:133], 0, v[4:5]
	v_add_u32_e32 v4, s4, v6
	v_ashrrev_i32_e32 v5, 31, v4
	v_lshl_add_u64 v[2:3], v[134:135], 0, s[6:7]
	v_lshlrev_b64 v[4:5], 6, v[4:5]
	v_or_b32_e32 v6, 16, v6
	v_lshl_add_u64 v[138:139], v[2:3], 0, v[4:5]
	v_add_u32_e32 v4, v6, v7
	v_min_i32_e32 v4, 0x2ffff, v4
	v_ashrrev_i32_e32 v5, 31, v4
	v_lshlrev_b64 v[4:5], 6, v[4:5]
	s_lshl_b32 s19, s9, 11
	v_lshl_add_u64 v[140:141], v[132:133], 0, v[4:5]
	v_add_u32_e32 v4, s4, v6
	s_mov_b32 m0, s19
	s_add_i32 s20, s19, 0x4000
	v_ashrrev_i32_e32 v5, 31, v4
	global_load_lds_dwordx4 v[136:137], off
	s_mov_b32 m0, s20
	s_or_b32 s21, s19, 0x400
	v_lshlrev_b64 v[4:5], 6, v[4:5]
	global_load_lds_dwordx4 v[138:139], off
	s_mov_b32 m0, s21
	s_add_i32 s22, s19, 0x4400
	s_lshr_b32 s5, s8, 7
	v_lshl_add_u64 v[142:143], v[2:3], 0, v[4:5]
	s_bfe_u32 s6, s8, 0x10006
	global_load_lds_dwordx4 v[140:141], off
	s_mov_b32 m0, s22
	s_mov_b64 s[8:9], 0xc00000
	s_add_i32 s15, s19, 0x8000
	global_load_lds_dwordx4 v[142:143], off
	v_lshl_add_u64 v[2:3], v[136:137], 0, s[8:9]
	s_mov_b32 m0, s15
	s_mov_b64 s[10:11], 0x10000
	s_add_i32 s16, s19, 0xc000
	global_load_lds_dwordx4 v[2:3], off
	v_lshl_add_u64 v[2:3], v[138:139], 0, s[10:11]
	s_mov_b32 m0, s16
	s_add_i32 s17, s19, 0x8400
	global_load_lds_dwordx4 v[2:3], off
	v_lshl_add_u64 v[2:3], v[140:141], 0, s[8:9]
	s_mov_b32 m0, s17
	s_add_i32 s18, s19, 0xc400
	global_load_lds_dwordx4 v[2:3], off
	v_lshl_add_u64 v[2:3], v[142:143], 0, s[10:11]
	s_mov_b32 m0, s18
	s_mov_b64 s[8:9], 0x1800000
	s_add_i32 s11, s19, 0x10000
	global_load_lds_dwordx4 v[2:3], off
	v_lshl_add_u64 v[2:3], v[136:137], 0, s[8:9]
	s_mov_b32 m0, s11
	s_mov_b64 s[24:25], 0x20000
	s_add_i32 s12, s19, 0x14000
	global_load_lds_dwordx4 v[2:3], off
	v_lshl_add_u64 v[2:3], v[138:139], 0, s[24:25]
	s_mov_b32 m0, s12
	s_add_i32 s13, s19, 0x10400
	global_load_lds_dwordx4 v[2:3], off
	v_lshl_add_u64 v[2:3], v[140:141], 0, s[8:9]
	s_mov_b32 m0, s13
	s_add_i32 s14, s19, 0x14400
	global_load_lds_dwordx4 v[2:3], off
	v_lshl_add_u64 v[2:3], v[142:143], 0, s[24:25]
	s_mov_b32 m0, s14
	s_mov_b64 s[26:27], 0x2400000
	global_load_lds_dwordx4 v[2:3], off
	s_mov_b64 s[14:15], 0x2400000
	v_lshl_add_u64 v[136:137], v[136:137], 0, s[14:15]
	v_lshl_add_u64 v[140:141], v[140:141], 0, s[14:15]
	s_mov_b64 s[14:15], 0x30000
	v_lshl_add_u64 v[138:139], v[138:139], 0, s[14:15]
	v_lshl_add_u64 v[142:143], v[142:143], 0, s[14:15]
	s_mov_b64 s[14:15], 0xc00000
	s_mov_b64 s[16:17], 0x10000
	s_lshl_b32 s23, s5, 12
	s_lshl_b32 s24, s6, 13
	s_mov_b32 s7, 0x18000
	v_mov_b32_e32 v2, 0
	v_mov_b32_e32 v3, v2
	v_mov_b32_e32 v4, v2
	v_mov_b32_e32 v5, v2
	v_mov_b32_e32 v6, v2
	v_mov_b32_e32 v7, v2
	v_mov_b32_e32 v8, v2
	v_mov_b32_e32 v9, v2
	v_mov_b32_e32 v10, v2
	v_mov_b32_e32 v11, v2
	v_mov_b32_e32 v12, v2
	v_mov_b32_e32 v13, v2
	v_mov_b32_e32 v14, v2
	v_mov_b32_e32 v15, v2
	v_mov_b32_e32 v16, v2
	v_mov_b32_e32 v17, v2
	v_mov_b32_e32 v18, v2
	v_mov_b32_e32 v19, v2
	v_mov_b32_e32 v20, v2
	v_mov_b32_e32 v21, v2
	v_mov_b32_e32 v22, v2
	v_mov_b32_e32 v23, v2
	v_mov_b32_e32 v24, v2
	v_mov_b32_e32 v25, v2
	v_mov_b32_e32 v26, v2
	v_mov_b32_e32 v27, v2
	v_mov_b32_e32 v28, v2
	v_mov_b32_e32 v29, v2
	v_mov_b32_e32 v30, v2
	v_mov_b32_e32 v31, v2
	v_mov_b32_e32 v32, v2
	v_mov_b32_e32 v33, v2
	v_mov_b32_e32 v34, v2
	v_mov_b32_e32 v35, v2
	v_mov_b32_e32 v36, v2
	v_mov_b32_e32 v37, v2
	v_mov_b32_e32 v38, v2
	v_mov_b32_e32 v39, v2
	v_mov_b32_e32 v40, v2
	v_mov_b32_e32 v41, v2
	v_mov_b32_e32 v42, v2
	v_mov_b32_e32 v43, v2
	v_mov_b32_e32 v44, v2
	v_mov_b32_e32 v45, v2
	v_mov_b32_e32 v46, v2
	v_mov_b32_e32 v47, v2
	v_mov_b32_e32 v48, v2
	v_mov_b32_e32 v49, v2
	v_mov_b32_e32 v50, v2
	v_mov_b32_e32 v51, v2
	v_mov_b32_e32 v52, v2
	v_mov_b32_e32 v53, v2
	v_mov_b32_e32 v54, v2
	v_mov_b32_e32 v55, v2
	v_mov_b32_e32 v56, v2
	v_mov_b32_e32 v57, v2
	v_mov_b32_e32 v58, v2
	v_mov_b32_e32 v59, v2
	v_mov_b32_e32 v60, v2
	v_mov_b32_e32 v61, v2
	v_mov_b32_e32 v62, v2
	v_mov_b32_e32 v63, v2
	v_mov_b32_e32 v64, v2
	v_mov_b32_e32 v65, v2
	v_mov_b32_e32 v66, v2
	v_mov_b32_e32 v67, v2
	v_mov_b32_e32 v68, v2
	v_mov_b32_e32 v69, v2
	v_mov_b32_e32 v70, v2
	v_mov_b32_e32 v71, v2
	v_mov_b32_e32 v72, v2
	v_mov_b32_e32 v73, v2
	v_mov_b32_e32 v74, v2
	v_mov_b32_e32 v75, v2
	v_mov_b32_e32 v76, v2
	v_mov_b32_e32 v77, v2
	v_mov_b32_e32 v78, v2
	v_mov_b32_e32 v79, v2
	v_mov_b32_e32 v80, v2
	v_mov_b32_e32 v81, v2
	v_mov_b32_e32 v82, v2
	v_mov_b32_e32 v83, v2
	v_mov_b32_e32 v84, v2
	v_mov_b32_e32 v85, v2
	v_mov_b32_e32 v86, v2
	v_mov_b32_e32 v87, v2
	v_mov_b32_e32 v88, v2
	v_mov_b32_e32 v89, v2
	v_mov_b32_e32 v90, v2
	v_mov_b32_e32 v91, v2
	v_mov_b32_e32 v92, v2
	v_mov_b32_e32 v93, v2
	v_mov_b32_e32 v94, v2
	v_mov_b32_e32 v95, v2
	v_mov_b32_e32 v96, v2
	v_mov_b32_e32 v97, v2
	v_mov_b32_e32 v98, v2
	v_mov_b32_e32 v99, v2
	v_mov_b32_e32 v100, v2
	v_mov_b32_e32 v101, v2
	v_mov_b32_e32 v102, v2
	v_mov_b32_e32 v103, v2
	v_mov_b32_e32 v104, v2
	v_mov_b32_e32 v105, v2
	v_mov_b32_e32 v106, v2
	v_mov_b32_e32 v107, v2
	v_mov_b32_e32 v108, v2
	v_mov_b32_e32 v109, v2
	v_mov_b32_e32 v110, v2
	v_mov_b32_e32 v111, v2
	v_mov_b32_e32 v112, v2
	v_mov_b32_e32 v113, v2
	v_mov_b32_e32 v114, v2
	v_mov_b32_e32 v115, v2
	v_mov_b32_e32 v116, v2
	v_mov_b32_e32 v117, v2
	v_mov_b32_e32 v118, v2
	v_mov_b32_e32 v119, v2
	v_mov_b32_e32 v120, v2
	v_mov_b32_e32 v121, v2
	v_mov_b32_e32 v122, v2
	v_mov_b32_e32 v123, v2
	v_mov_b32_e32 v124, v2
	v_mov_b32_e32 v125, v2
	v_mov_b32_e32 v126, v2
	v_mov_b32_e32 v127, v2
	v_mov_b32_e32 v128, v2
	v_mov_b32_e32 v129, v2
	s_waitcnt vmcnt(8)
	s_barrier
	s_add_i32 s9, s7, 0xfffe8000
	s_and_b32 s9, s9, 0x18000
	s_add_i32 s10, s9, s23
	s_or_b32 s9, s9, s24
	v_add_u32_e32 v222, s10, v130
	v_add_u32_e32 v223, s9, v130
	ds_read_b128 v[174:177], v222
	ds_read_b128 v[182:185], v223 offset:16384
	ds_read_b128 v[178:181], v222 offset:2048
	ds_read_b128 v[186:189], v223 offset:18432
	ds_read_b128 v[190:193], v223 offset:20480
	ds_read_b128 v[194:197], v223 offset:22528
	.p2align 6
; #define MFMA(a, b, c) __builtin_amdgcn_mfma_f32_32x32x16_bf16((a), (b), (c), 0, 0, 0)
; DI unsigned pk2(float a, float b) { fl2_t f = {a, b}; bf2_t r = __builtin_convertvector(f, bf2_t); return __builtin_bit_cast(unsigned, r); }
; #define WAIT_V(n) asm volatile("s_waitcnt vmcnt(%0)" ::"n"(n) : "memory")
; #define RAW_BARRIER() do { asm volatile("s_waitcnt lgkmcnt(0)" ::: "memory"); __builtin_amdgcn_s_barrier(); } while (0)
; template <typename FA, typename FB, typename FE>
; DI void gemm_tile(char* lds, int K, int astride, int bstride, FA arow, FB brow, FE epi) {
;     ...
;   for (int kt = 0; kt < nk; ++kt) {
;     if (kt + 2 < nk) WAIT_V(8); else if (kt + 1 < nk) WAIT_V(4); else WAIT_V(0);
;     RAW_BARRIER();
;     if (kt + 3 < nk) stage((kt + 3) & 3, kt + 3);
;     const char* sa = lds + (kt & 3) * 32768 + wm * 4096;
;     const char* sb = lds + (kt & 3) * 32768 + 16384 + wn * 8192;
; #pragma unroll
;     for (int ks = 0; ks < 2; ++ks) {
;       bf16x8 a0 = *(const bf16x8*)(sa + foff[ks]), a1 = *(const bf16x8*)(sa + 2048 + foff[ks]);
; #pragma unroll
;       for (int nt = 0; nt < 4; ++nt) {
;         bf16x8 bb = *(const bf16x8*)(sb + nt * 2048 + foff[ks]);
;         acc[0][nt] = MFMA(a0, bb, acc[0][nt]);
;         acc[1][nt] = MFMA(a1, bb, acc[1][nt]);
;       }
;     }
;   }
;   RAW_BARRIER();
;   bfr* Cs = (bfr*)lds;
; #pragma unroll
;   for (int mt = 0; mt < 2; ++mt)
; #pragma unroll
;     for (int nt = 0; nt < 4; ++nt)
; #pragma unroll
;       for (int i = 0; i < 16; i += 2) {
;         const int row = wm * 64 + mt * 32 + (i & 3) + 8 * (i >> 2) + 4 * h8;
;         const unsigned pr = pk2(acc[mt][nt][i], acc[mt][nt][i + 1]);
;         Cs[row * CSS + wn * 128 + nt * 32 + r] = (bfr)(pr & 0xffffu);
;         Cs[(row + 1) * CSS + wn * 128 + nt * 32 + r] = (bfr)(pr >> 16);
;       }
.Lgf_P7_loop:
	s_and_b32 s8, s7, 0x18000
	s_add_i32 s8, s19, s8
	s_cmp_lt_u32 s7, 0x80000
	s_cselect_b64 s[12:13], -1, 0
	s_cmp_ge_u32 s7, 0x88000
	s_cbranch_scc1 .Lgf_P7_w0
	s_waitcnt vmcnt(4)
	s_branch .Lgf_P7_wd
.Lgf_P7_w0:
	s_waitcnt vmcnt(0)
.Lgf_P7_wd:
	s_mov_b32 m0, s8
	s_barrier
	s_add_i32 s9, s7, 0xfffe8000
	s_and_b32 s9, s9, 0x18000
	s_add_i32 s10, s9, s23
	s_or_b32 s9, s9, s24
	v_add_u32_e32 v224, s10, v146
	v_add_u32_e32 v225, s9, v146
	s_waitcnt lgkmcnt(4)
	v_mfma_f32_32x32x16_bf16 v[114:129], v[174:177], v[182:185], v[114:129]
	s_mov_b64 exec, s[12:13]
	global_load_lds_dwordx4 v[136:137], off
	s_mov_b64 exec, -1
	s_add_i32 m0, s8, 0x4000
	ds_read_b128 v[198:201], v224
	s_waitcnt lgkmcnt(4)
	v_mfma_f32_32x32x16_bf16 v[50:65], v[178:181], v[182:185], v[50:65]
	s_mov_b64 exec, s[12:13]
	global_load_lds_dwordx4 v[138:139], off
	s_mov_b64 exec, -1
	s_add_i32 m0, s8, 0x400
	ds_read_b128 v[206:209], v225 offset:16384
	s_waitcnt lgkmcnt(4)
	v_mfma_f32_32x32x16_bf16 v[98:113], v[174:177], v[186:189], v[98:113]
	s_mov_b64 exec, s[12:13]
	global_load_lds_dwordx4 v[140:141], off
	s_mov_b64 exec, -1
	s_add_i32 m0, s8, 0x4400
	ds_read_b128 v[202:205], v224 offset:2048
	v_mfma_f32_32x32x16_bf16 v[34:49], v[178:181], v[186:189], v[34:49]
	ds_read_b128 v[210:213], v225 offset:18432
	s_mov_b64 exec, s[12:13]
	global_load_lds_dwordx4 v[142:143], off
	s_mov_b64 exec, -1
	s_waitcnt lgkmcnt(5)
	v_mfma_f32_32x32x16_bf16 v[82:97], v[174:177], v[190:193], v[82:97]
	ds_read_b128 v[214:217], v225 offset:20480
	v_lshl_add_u64 v[138:139], v[138:139], 0, s[16:17]
	v_lshl_add_u64 v[142:143], v[142:143], 0, s[16:17]
	v_mfma_f32_32x32x16_bf16 v[18:33], v[178:181], v[190:193], v[18:33]
	ds_read_b128 v[218:221], v225 offset:22528
	v_lshl_add_u64 v[136:137], v[136:137], 0, s[14:15]
	v_lshl_add_u64 v[140:141], v[140:141], 0, s[14:15]
	s_waitcnt lgkmcnt(6)
	v_mfma_f32_32x32x16_bf16 v[66:81], v[174:177], v[194:197], v[66:81]
	s_add_i32 s9, s7, 0xffff0000
	s_and_b32 s9, s9, 0x18000
	s_add_i32 s10, s9, s23
	s_or_b32 s9, s9, s24
	v_mfma_f32_32x32x16_bf16 v[2:17], v[178:181], v[194:197], v[2:17]
	v_add_u32_e32 v222, s10, v130
	v_add_u32_e32 v223, s9, v130
	s_waitcnt lgkmcnt(4)
	v_mfma_f32_32x32x16_bf16 v[114:129], v[198:201], v[206:209], v[114:129]
	ds_read_b128 v[174:177], v222
	s_waitcnt lgkmcnt(4)
	v_mfma_f32_32x32x16_bf16 v[50:65], v[202:205], v[206:209], v[50:65]
	ds_read_b128 v[182:185], v223 offset:16384
	s_waitcnt lgkmcnt(4)
	v_mfma_f32_32x32x16_bf16 v[98:113], v[198:201], v[210:213], v[98:113]
	ds_read_b128 v[178:181], v222 offset:2048
	v_mfma_f32_32x32x16_bf16 v[34:49], v[202:205], v[210:213], v[34:49]
	ds_read_b128 v[186:189], v223 offset:18432
	s_waitcnt lgkmcnt(5)
	v_mfma_f32_32x32x16_bf16 v[82:97], v[198:201], v[214:217], v[82:97]
	ds_read_b128 v[190:193], v223 offset:20480
	v_mfma_f32_32x32x16_bf16 v[18:33], v[202:205], v[214:217], v[18:33]
	ds_read_b128 v[194:197], v223 offset:22528
	s_waitcnt lgkmcnt(6)
	v_mfma_f32_32x32x16_bf16 v[66:81], v[198:201], v[218:221], v[66:81]
	s_add_i32 s7, s7, 0x8000
	v_mfma_f32_32x32x16_bf16 v[2:17], v[202:205], v[218:221], v[2:17]
	s_cmp_eq_u32 s7, 0x98000
	s_cbranch_scc0 .Lgf_P7_loop
	s_waitcnt lgkmcnt(0)
	s_barrier
	s_nop 15
	s_nop 10
	v_cvt_pk_bf16_f32 v98, v98, v99
	v_lshl_or_b32 v136, s5, 6, v147
	v_cvt_pk_bf16_f32 v137, v114, v115
	v_lshl_or_b32 v114, s6, 8, v171
	s_movk_i32 s5, 0x210
	v_mad_u64_u32 v[114:115], s[6:7], v136, s5, v[114:115]
	v_cvt_pk_bf16_f32 v115, v116, v117
	ds_write_b16 v114, v137
	ds_write_b16_d16_hi v114, v137 offset:528
	ds_write_b16 v114, v115 offset:1056
	ds_write_b16_d16_hi v114, v115 offset:1584
	v_cvt_pk_bf16_f32 v115, v118, v119
	ds_write_b16 v114, v115 offset:4224
	ds_write_b16_d16_hi v114, v115 offset:4752
	v_cvt_pk_bf16_f32 v115, v120, v121
	ds_write_b16 v114, v115 offset:5280
	ds_write_b16_d16_hi v114, v115 offset:5808
	v_cvt_pk_bf16_f32 v115, v122, v123
	ds_write_b16 v114, v115 offset:8448
	ds_write_b16_d16_hi v114, v115 offset:8976
	v_cvt_pk_bf16_f32 v115, v124, v125
	ds_write_b16 v114, v115 offset:9504
	ds_write_b16_d16_hi v114, v115 offset:10032
	v_cvt_pk_bf16_f32 v115, v126, v127
	ds_write_b16 v114, v115 offset:12672
	ds_write_b16_d16_hi v114, v115 offset:13200
	v_cvt_pk_bf16_f32 v115, v128, v129
	ds_write_b16 v114, v115 offset:13728
	ds_write_b16_d16_hi v114, v115 offset:14256
	ds_write_b16 v114, v98 offset:64
	ds_write_b16_d16_hi v114, v98 offset:592
	v_cvt_pk_bf16_f32 v98, v100, v101
	ds_write_b16 v114, v98 offset:1120
	ds_write_b16_d16_hi v114, v98 offset:1648
	v_cvt_pk_bf16_f32 v98, v102, v103
	ds_write_b16 v114, v98 offset:4288
	ds_write_b16_d16_hi v114, v98 offset:4816
	v_cvt_pk_bf16_f32 v98, v104, v105
	ds_write_b16 v114, v98 offset:5344
	ds_write_b16_d16_hi v114, v98 offset:5872
	v_cvt_pk_bf16_f32 v98, v106, v107
	ds_write_b16 v114, v98 offset:8512
	ds_write_b16_d16_hi v114, v98 offset:9040
	v_cvt_pk_bf16_f32 v98, v108, v109
	ds_write_b16 v114, v98 offset:9568
	ds_write_b16_d16_hi v114, v98 offset:10096
	v_cvt_pk_bf16_f32 v98, v110, v111
	ds_write_b16 v114, v98 offset:12736
	ds_write_b16_d16_hi v114, v98 offset:13264
	v_cvt_pk_bf16_f32 v98, v112, v113
	v_cvt_pk_bf16_f32 v82, v82, v83
	ds_write_b16 v114, v98 offset:13792
	ds_write_b16_d16_hi v114, v98 offset:14320
	ds_write_b16 v114, v82 offset:128
	ds_write_b16_d16_hi v114, v82 offset:656
	v_cvt_pk_bf16_f32 v82, v84, v85
	ds_write_b16 v114, v82 offset:1184
	ds_write_b16_d16_hi v114, v82 offset:1712
	v_cvt_pk_bf16_f32 v82, v86, v87
	ds_write_b16 v114, v82 offset:4352
	ds_write_b16_d16_hi v114, v82 offset:4880
	v_cvt_pk_bf16_f32 v82, v88, v89
	ds_write_b16 v114, v82 offset:5408
	ds_write_b16_d16_hi v114, v82 offset:5936
; DI unsigned pk2(float a, float b) { fl2_t f = {a, b}; bf2_t r = __builtin_convertvector(f, bf2_t); return __builtin_bit_cast(unsigned, r); }
; template <typename FA, typename FB, typename FE>
; DI void gemm_tile(char* lds, int K, int astride, int bstride, FA arow, FB brow, FE epi) {
;     ...
; #pragma unroll
;   for (int mt = 0; mt < 2; ++mt)
; #pragma unroll
;     for (int nt = 0; nt < 4; ++nt)
; #pragma unroll
;       for (int i = 0; i < 16; i += 2) {
;         const int row = wm * 64 + mt * 32 + (i & 3) + 8 * (i >> 2) + 4 * h8;
;         const unsigned pr = pk2(acc[mt][nt][i], acc[mt][nt][i + 1]);
;         Cs[row * CSS + wn * 128 + nt * 32 + r] = (bfr)(pr & 0xffffu);
;         Cs[(row + 1) * CSS + wn * 128 + nt * 32 + r] = (bfr)(pr >> 16);
;       }
;   __syncthreads();
	v_cvt_pk_bf16_f32 v82, v90, v91
	ds_write_b16 v114, v82 offset:8576
	ds_write_b16_d16_hi v114, v82 offset:9104
	v_cvt_pk_bf16_f32 v82, v92, v93
	ds_write_b16 v114, v82 offset:9632
	ds_write_b16_d16_hi v114, v82 offset:10160
	v_cvt_pk_bf16_f32 v82, v94, v95
	ds_write_b16 v114, v82 offset:12800
	ds_write_b16_d16_hi v114, v82 offset:13328
	v_cvt_pk_bf16_f32 v82, v96, v97
	v_cvt_pk_bf16_f32 v66, v66, v67
	ds_write_b16 v114, v82 offset:13856
	ds_write_b16_d16_hi v114, v82 offset:14384
	ds_write_b16 v114, v66 offset:192
	ds_write_b16_d16_hi v114, v66 offset:720
	v_cvt_pk_bf16_f32 v66, v68, v69
	ds_write_b16 v114, v66 offset:1248
	ds_write_b16_d16_hi v114, v66 offset:1776
	v_cvt_pk_bf16_f32 v66, v70, v71
	ds_write_b16 v114, v66 offset:4416
	ds_write_b16_d16_hi v114, v66 offset:4944
	v_cvt_pk_bf16_f32 v66, v72, v73
	ds_write_b16 v114, v66 offset:5472
	ds_write_b16_d16_hi v114, v66 offset:6000
	v_cvt_pk_bf16_f32 v66, v74, v75
	ds_write_b16 v114, v66 offset:8640
	ds_write_b16_d16_hi v114, v66 offset:9168
	v_cvt_pk_bf16_f32 v66, v76, v77
	ds_write_b16 v114, v66 offset:9696
	ds_write_b16_d16_hi v114, v66 offset:10224
	v_cvt_pk_bf16_f32 v66, v78, v79
	ds_write_b16 v114, v66 offset:12864
	ds_write_b16_d16_hi v114, v66 offset:13392
	v_cvt_pk_bf16_f32 v66, v80, v81
	v_cvt_pk_bf16_f32 v50, v50, v51
	ds_write_b16 v114, v66 offset:13920
	ds_write_b16_d16_hi v114, v66 offset:14448
	ds_write_b16 v114, v50 offset:16896
	ds_write_b16_d16_hi v114, v50 offset:17424
	v_cvt_pk_bf16_f32 v50, v52, v53
	ds_write_b16 v114, v50 offset:17952
	ds_write_b16_d16_hi v114, v50 offset:18480
	v_cvt_pk_bf16_f32 v50, v54, v55
	ds_write_b16 v114, v50 offset:21120
	ds_write_b16_d16_hi v114, v50 offset:21648
	v_cvt_pk_bf16_f32 v50, v56, v57
	ds_write_b16 v114, v50 offset:22176
	ds_write_b16_d16_hi v114, v50 offset:22704
	v_cvt_pk_bf16_f32 v50, v58, v59
	ds_write_b16 v114, v50 offset:25344
	ds_write_b16_d16_hi v114, v50 offset:25872
	v_cvt_pk_bf16_f32 v50, v60, v61
	ds_write_b16 v114, v50 offset:26400
	ds_write_b16_d16_hi v114, v50 offset:26928
	v_cvt_pk_bf16_f32 v50, v62, v63
	ds_write_b16 v114, v50 offset:29568
	ds_write_b16_d16_hi v114, v50 offset:30096
	v_cvt_pk_bf16_f32 v50, v64, v65
	v_cvt_pk_bf16_f32 v34, v34, v35
	ds_write_b16 v114, v50 offset:30624
	ds_write_b16_d16_hi v114, v50 offset:31152
	ds_write_b16 v114, v34 offset:16960
	ds_write_b16_d16_hi v114, v34 offset:17488
	v_cvt_pk_bf16_f32 v34, v36, v37
	ds_write_b16 v114, v34 offset:18016
	ds_write_b16_d16_hi v114, v34 offset:18544
	v_cvt_pk_bf16_f32 v34, v38, v39
	ds_write_b16 v114, v34 offset:21184
	ds_write_b16_d16_hi v114, v34 offset:21712
	v_cvt_pk_bf16_f32 v34, v40, v41
	ds_write_b16 v114, v34 offset:22240
	ds_write_b16_d16_hi v114, v34 offset:22768
	v_cvt_pk_bf16_f32 v34, v42, v43
	ds_write_b16 v114, v34 offset:25408
	ds_write_b16_d16_hi v114, v34 offset:25936
	v_cvt_pk_bf16_f32 v34, v44, v45
	ds_write_b16 v114, v34 offset:26464
	ds_write_b16_d16_hi v114, v34 offset:26992
	v_cvt_pk_bf16_f32 v34, v46, v47
	ds_write_b16 v114, v34 offset:29632
	ds_write_b16_d16_hi v114, v34 offset:30160
	v_cvt_pk_bf16_f32 v34, v48, v49
	v_cvt_pk_bf16_f32 v18, v18, v19
	ds_write_b16 v114, v34 offset:30688
	ds_write_b16_d16_hi v114, v34 offset:31216
	ds_write_b16 v114, v18 offset:17024
	ds_write_b16_d16_hi v114, v18 offset:17552
	v_cvt_pk_bf16_f32 v18, v20, v21
	ds_write_b16 v114, v18 offset:18080
	ds_write_b16_d16_hi v114, v18 offset:18608
	v_cvt_pk_bf16_f32 v18, v22, v23
	ds_write_b16 v114, v18 offset:21248
	ds_write_b16_d16_hi v114, v18 offset:21776
	v_cvt_pk_bf16_f32 v18, v24, v25
	ds_write_b16 v114, v18 offset:22304
	ds_write_b16_d16_hi v114, v18 offset:22832
	v_cvt_pk_bf16_f32 v18, v26, v27
	ds_write_b16 v114, v18 offset:25472
	ds_write_b16_d16_hi v114, v18 offset:26000
	v_cvt_pk_bf16_f32 v18, v28, v29
	ds_write_b16 v114, v18 offset:26528
	ds_write_b16_d16_hi v114, v18 offset:27056
	v_cvt_pk_bf16_f32 v18, v30, v31
	ds_write_b16 v114, v18 offset:29696
	ds_write_b16_d16_hi v114, v18 offset:30224
	v_cvt_pk_bf16_f32 v18, v32, v33
	v_cvt_pk_bf16_f32 v2, v2, v3
	ds_write_b16 v114, v18 offset:30752
	ds_write_b16_d16_hi v114, v18 offset:31280
	ds_write_b16 v114, v2 offset:17088
	ds_write_b16_d16_hi v114, v2 offset:17616
	v_cvt_pk_bf16_f32 v2, v4, v5
	ds_write_b16 v114, v2 offset:18144
	ds_write_b16_d16_hi v114, v2 offset:18672
	v_cvt_pk_bf16_f32 v2, v6, v7
	ds_write_b16 v114, v2 offset:21312
	ds_write_b16_d16_hi v114, v2 offset:21840
	v_cvt_pk_bf16_f32 v2, v8, v9
	ds_write_b16 v114, v2 offset:22368
	ds_write_b16_d16_hi v114, v2 offset:22896
	v_cvt_pk_bf16_f32 v2, v10, v11
	ds_write_b16 v114, v2 offset:25536
	ds_write_b16_d16_hi v114, v2 offset:26064
	v_cvt_pk_bf16_f32 v2, v12, v13
	ds_write_b16 v114, v2 offset:26592
	ds_write_b16_d16_hi v114, v2 offset:27120
	v_cvt_pk_bf16_f32 v2, v14, v15
	ds_write_b16 v114, v2 offset:29760
	ds_write_b16_d16_hi v114, v2 offset:30288
	v_cvt_pk_bf16_f32 v2, v16, v17
	ds_write_b16 v114, v2 offset:30816
	ds_write_b16_d16_hi v114, v2 offset:31344
	s_waitcnt vmcnt(0) lgkmcnt(0)
	s_barrier
; DI unsigned pk2(float a, float b) { fl2_t f = {a, b}; bf2_t r = __builtin_convertvector(f, bf2_t); return __builtin_bit_cast(unsigned, r); }
; DI void phase_moe(const Params& p, char* lds, int mode) {
;     ...
;         if (mode == 1) {
;           float gt[16]; int tk[16];
; #pragma unroll
;           for (int ps = 0; ps < 16; ++ps) {
;             const int grow = half * 128 + ps * 8 + (tid >> 5);
;             tk[ps] = rowtok[grow];
;             gt[ps] = gate[(size_t)k * T + tk[ps]];
;           }
;           asm volatile("" ::: "memory");
; #pragma unroll
;           for (int ps = 0; ps < 16; ++ps) {
;             const int row = ps * 8 + (tid >> 5);
;             if (r0 + half * 128 + row < n) {
;               float4 c = cs4(Cs, row, c4);
;               const float g = gt[ps];
;               u32x2 o; o[0] = pk2(g * c.x, g * c.y); o[1] = pk2(g * c.z, g * c.w);
;               *(u32x2*)(Y0 + (size_t)tk[ps] * D + col) = o;
;             }
;           }
	ds_read2_b32 v[4:5], v150 offset1:8
	v_or_b32_e32 v2, s4, v148
	v_ashrrev_i32_e32 v3, 31, v2
	s_waitcnt lgkmcnt(0)
	v_ashrrev_i32_e32 v57, 31, v5
	v_mov_b32_e32 v56, v5
	v_ashrrev_i32_e32 v65, 31, v4
	v_mov_b32_e32 v64, v4
	v_lshl_add_u64 v[4:5], v[56:57], 2, s[50:51]
	global_load_dword v60, v[4:5], off
	ds_read2_b32 v[4:5], v150 offset0:16 offset1:24
	v_lshl_add_u64 v[6:7], v[64:65], 2, s[50:51]
	global_load_dword v66, v[6:7], off
	s_waitcnt lgkmcnt(0)
	v_ashrrev_i32_e32 v49, 31, v5
	v_mov_b32_e32 v48, v5
	v_ashrrev_i32_e32 v59, 31, v4
	v_mov_b32_e32 v58, v4
	v_lshl_add_u64 v[4:5], v[48:49], 2, s[50:51]
	global_load_dword v52, v[4:5], off
	ds_read2_b32 v[4:5], v150 offset0:32 offset1:40
	v_lshl_add_u64 v[6:7], v[58:59], 2, s[50:51]
	global_load_dword v62, v[6:7], off
	s_waitcnt lgkmcnt(0)
	v_ashrrev_i32_e32 v43, 31, v5
	v_mov_b32_e32 v42, v5
	v_ashrrev_i32_e32 v51, 31, v4
	v_mov_b32_e32 v50, v4
	v_lshl_add_u64 v[4:5], v[42:43], 2, s[50:51]
	global_load_dword v46, v[4:5], off
	ds_read2_b32 v[4:5], v150 offset0:48 offset1:56
	v_lshl_add_u64 v[6:7], v[50:51], 2, s[50:51]
	global_load_dword v54, v[6:7], off
	s_waitcnt lgkmcnt(0)
	v_ashrrev_i32_e32 v35, 31, v5
	v_mov_b32_e32 v34, v5
	v_ashrrev_i32_e32 v41, 31, v4
	v_mov_b32_e32 v40, v4
	v_lshl_add_u64 v[4:5], v[34:35], 2, s[50:51]
	global_load_dword v38, v[4:5], off
	ds_read2_b32 v[4:5], v150 offset0:64 offset1:72
	v_lshl_add_u64 v[6:7], v[40:41], 2, s[50:51]
	global_load_dword v44, v[6:7], off
	s_waitcnt lgkmcnt(0)
	v_ashrrev_i32_e32 v27, 31, v5
	v_mov_b32_e32 v26, v5
	v_ashrrev_i32_e32 v33, 31, v4
	v_mov_b32_e32 v32, v4
	v_lshl_add_u64 v[4:5], v[26:27], 2, s[50:51]
	global_load_dword v30, v[4:5], off
	ds_read2_b32 v[4:5], v150 offset0:80 offset1:88
	v_lshl_add_u64 v[6:7], v[32:33], 2, s[50:51]
	global_load_dword v36, v[6:7], off
	s_waitcnt lgkmcnt(0)
	v_ashrrev_i32_e32 v19, 31, v5
	v_mov_b32_e32 v18, v5
	v_ashrrev_i32_e32 v25, 31, v4
	v_mov_b32_e32 v24, v4
	v_lshl_add_u64 v[4:5], v[18:19], 2, s[50:51]
	global_load_dword v22, v[4:5], off
	ds_read2_b32 v[4:5], v150 offset0:96 offset1:104
	v_lshl_add_u64 v[6:7], v[24:25], 2, s[50:51]
	global_load_dword v28, v[6:7], off
	s_waitcnt lgkmcnt(0)
	v_ashrrev_i32_e32 v17, 31, v4
	v_mov_b32_e32 v16, v4
	v_lshl_add_u64 v[6:7], v[16:17], 2, s[50:51]
	global_load_dword v20, v[6:7], off
	ds_read2_b32 v[6:7], v150 offset0:112 offset1:120
	v_ashrrev_i32_e32 v11, 31, v5
	v_mov_b32_e32 v10, v5
	v_lshl_add_u64 v[4:5], v[10:11], 2, s[50:51]
	global_load_dword v14, v[4:5], off
	s_waitcnt lgkmcnt(0)
	v_ashrrev_i32_e32 v9, 31, v6
	v_mov_b32_e32 v8, v6
	v_lshl_add_u64 v[4:5], v[8:9], 2, s[50:51]
	global_load_dword v12, v[4:5], off
	v_ashrrev_i32_e32 v5, 31, v7
	v_mov_b32_e32 v4, v7
	v_lshl_add_u64 v[6:7], v[4:5], 2, s[50:51]
	global_load_dword v6, v[6:7], off
	v_add_u32_e32 v7, v173, v149
	v_cmp_lt_i32_e64 s[26:27], v7, v172
	s_and_saveexec_b64 s[4:5], s[26:27]
	s_cbranch_execz .LBB0_334
	ds_read_b64 v[68:69], v151
	v_lshlrev_b64 v[64:65], 11, v[64:65]
	v_lshl_add_u64 v[64:65], s[48:49], 0, v[64:65]
	v_lshl_add_u64 v[64:65], v[2:3], 1, v[64:65]
	s_waitcnt lgkmcnt(0)
	v_lshlrev_b32_e32 v70, 16, v68
	v_and_b32_e32 v71, 0xffff0000, v68
	v_lshlrev_b32_e32 v68, 16, v69
	v_and_b32_e32 v69, 0xffff0000, v69
	s_waitcnt vmcnt(14)
	v_pk_mul_f32 v[70:71], v[66:67], v[70:71] op_sel_hi:[0,1]
	v_pk_mul_f32 v[66:67], v[66:67], v[68:69] op_sel_hi:[0,1]
	v_cvt_pk_bf16_f32 v68, v70, v71
	v_cvt_pk_bf16_f32 v69, v66, v67
	global_store_dwordx2 v[64:65], v[68:69], off

; DI void dma16(const void* src, void* lds_wave_base) { __builtin_amdgcn_global_load_lds((const unsigned*)src, (unsigned*)lds_wave_base, 16, 0, 0); }
; #define WAIT_V(n) asm volatile("s_waitcnt vmcnt(%0)" ::"n"(n) : "memory")
; #define RAW_BARRIER() do { asm volatile("s_waitcnt lgkmcnt(0)" ::: "memory"); __builtin_amdgcn_s_barrier(); } while (0)
; template <typename FA, typename FB, typename FE>
; DI void gemm_tile(char* lds, int K, int astride, int bstride, FA arow, FB brow, FE epi) {
;   const int tid = threadIdx.x, w = __builtin_amdgcn_readfirstlane(tid >> 6), lane = tid & 63, r = lane & 31, h8 = lane >> 5;
;   const int wm = w >> 1, wn = w & 1;
;   const bfr* ap[2]; const bfr* bp[2];
; #pragma unroll
;   for (int i = 0; i < 2; ++i) {
;     const int row = (w * 2 + i) * 16 + (lane >> 2);
;     const int sw = ((lane & 3) ^ ((row >> 2) & 3)) * 8;
;     ap[i] = arow(row) + sw;
;     bp[i] = brow(row) + sw;
;   }
;   int foff[2];
; #pragma unroll
;   for (int ks = 0; ks < 2; ++ks) foff[ks] = r * 64 + (((ks * 2 + h8) ^ ((r >> 2) & 3)) << 4);
;   f32x16 acc[2][4];
; #pragma unroll
;   for (int a = 0; a < 2; ++a)
; #pragma unroll
;     for (int b = 0; b < 4; ++b)
; #pragma unroll
;       for (int i = 0; i < 16; ++i) acc[a][b][i] = 0.f;
;   const int nk = K >> 5;
;   auto stage = [&](int buf, int kt) {
;     char* sa = lds + buf * 32768;
; #pragma unroll
;     for (int i = 0; i < 2; ++i) {
;       dma16(ap[i] + (size_t)kt * astride, sa + (w * 2 + i) * 1024);
;       dma16(bp[i] + (size_t)kt * bstride, sa + 16384 + (w * 2 + i) * 1024);
;     }
;   };
;   stage(0, 0); stage(1, 1); stage(2, 2);
;   for (int kt = 0; kt < nk; ++kt) {
;     if (kt + 2 < nk) WAIT_V(8); else if (kt + 1 < nk) WAIT_V(4); else WAIT_V(0);
;     RAW_BARRIER();
; DI void phase_moe(const Params& p, char* lds, int mode) {
;     ...
;     if (mode == 2) {
;       for (int i = tid; i < NBR * 64; i += NT) {
;         const int brr = i >> 6, cc = (i & 63) * 4;
;         *(float4*)(g2t + brr * 256 + cc) = *(const float4*)(mod + brr * 6144 + 5 * 1024 + nt2 * 256 + cc);
;       }
;     }
;     __syncthreads();
.LBB0_427:
	global_load_dwordx4 v[4:7], v[0:1], off
	v_lshl_add_u64 v[0:1], v[0:1], 0, s[50:51]
	global_load_dwordx4 v[248:251], v[0:1], off
	v_lshl_add_u64 v[0:1], v[0:1], 0, s[50:51]
	v_add_u32_e32 v3, 0x400, v3
	s_movk_i32 s1, 0x27f
	v_cmp_ge_u32_e32 vcc, s1, v3
	s_nop 1
	s_and_saveexec_b64 s[6:7], vcc
	global_load_dwordx4 v[252:255], v[0:1], off
	s_or_b64 exec, exec, s[6:7]
	s_waitcnt vmcnt(0)
	ds_write_b128 v2, v[4:7]
	ds_write_b128 v2, v[248:251] offset:8192
	s_and_saveexec_b64 s[6:7], vcc
	ds_write_b128 v2, v[252:255] offset:16384
	s_or_b64 exec, exec, s[6:7]
	s_mov_b64 s[6:7], 0
	s_or_b64 exec, exec, s[6:7]
	s_lshl_b32 s8, s48, 2
	s_add_i32 s8, s8, 0x25e00
	v_mov_b32_e32 v0, s8
	s_waitcnt lgkmcnt(0)
	s_barrier
	ds_read_b32 v0, v0
	v_readfirstlane_b32 s6, v186
	s_lshr_b32 s7, s6, 6
	v_lshl_or_b32 v4, s7, 5, v188
	s_mov_b32 s5, s49
	s_waitcnt lgkmcnt(0)
	v_add_u32_e32 v5, v0, v153
	v_add_u32_e32 v2, v4, v5
	v_min_i32_e32 v2, 0x2ffff, v2
	v_ashrrev_i32_e32 v3, 31, v2
	v_lshlrev_b64 v[2:3], 6, v[2:3]
	v_lshl_add_u64 v[136:137], v[130:131], 0, v[2:3]
	v_add_u32_e32 v2, s0, v4
	s_lshl_b64 s[4:5], s[4:5], 20
	v_ashrrev_i32_e32 v3, 31, v2
	v_lshl_add_u64 v[0:1], v[132:133], 0, s[4:5]
	v_lshlrev_b64 v[2:3], 6, v[2:3]
	v_or_b32_e32 v4, 16, v4
	v_lshl_add_u64 v[138:139], v[0:1], 0, v[2:3]
	v_add_u32_e32 v2, v4, v5
	v_min_i32_e32 v2, 0x2ffff, v2
	v_ashrrev_i32_e32 v3, 31, v2
	v_lshlrev_b64 v[2:3], 6, v[2:3]
	s_lshl_b32 s17, s7, 11
	v_lshl_add_u64 v[140:141], v[130:131], 0, v[2:3]
	v_add_u32_e32 v2, s0, v4
	s_mov_b32 m0, s17
	s_add_i32 s18, s17, 0x4000
	v_ashrrev_i32_e32 v3, 31, v2
	global_load_lds_dwordx4 v[136:137], off
	s_mov_b32 m0, s18
	s_or_b32 s19, s17, 0x400
	v_lshlrev_b64 v[2:3], 6, v[2:3]
	global_load_lds_dwordx4 v[138:139], off
	s_mov_b32 m0, s19
	s_add_i32 s20, s17, 0x4400
	s_lshr_b32 s1, s6, 7
	v_lshl_add_u64 v[142:143], v[0:1], 0, v[2:3]
	s_bfe_u32 s4, s6, 0x10006
	global_load_lds_dwordx4 v[140:141], off
	s_mov_b32 m0, s20
	s_mov_b64 s[6:7], 0xc00000
	s_add_i32 s13, s17, 0x8000
	global_load_lds_dwordx4 v[142:143], off
	v_lshl_add_u64 v[0:1], v[136:137], 0, s[6:7]
	s_mov_b32 m0, s13
	s_mov_b64 s[8:9], 0x10000
	s_add_i32 s14, s17, 0xc000
	global_load_lds_dwordx4 v[0:1], off
	v_lshl_add_u64 v[0:1], v[138:139], 0, s[8:9]
	s_mov_b32 m0, s14
	s_add_i32 s15, s17, 0x8400
	global_load_lds_dwordx4 v[0:1], off
	v_lshl_add_u64 v[0:1], v[140:141], 0, s[6:7]
	s_mov_b32 m0, s15
	s_add_i32 s16, s17, 0xc400
	global_load_lds_dwordx4 v[0:1], off
	v_lshl_add_u64 v[0:1], v[142:143], 0, s[8:9]
	s_mov_b32 m0, s16
	s_mov_b64 s[6:7], 0x1800000
	s_add_i32 s9, s17, 0x10000
	global_load_lds_dwordx4 v[0:1], off
	v_lshl_add_u64 v[0:1], v[136:137], 0, s[6:7]
	s_mov_b32 m0, s9
	s_mov_b64 s[22:23], 0x20000
	s_add_i32 s10, s17, 0x14000
	global_load_lds_dwordx4 v[0:1], off
	v_lshl_add_u64 v[0:1], v[138:139], 0, s[22:23]
	s_mov_b32 m0, s10
	s_add_i32 s11, s17, 0x10400
	global_load_lds_dwordx4 v[0:1], off
	v_lshl_add_u64 v[0:1], v[140:141], 0, s[6:7]
	s_mov_b32 m0, s11
	s_add_i32 s12, s17, 0x14400
	global_load_lds_dwordx4 v[0:1], off
	v_lshl_add_u64 v[0:1], v[142:143], 0, s[22:23]
	s_mov_b32 m0, s12
	s_mov_b64 s[24:25], 0x2400000
	global_load_lds_dwordx4 v[0:1], off
	s_mov_b64 s[12:13], 0x2400000
	v_lshl_add_u64 v[136:137], v[136:137], 0, s[12:13]
	v_lshl_add_u64 v[140:141], v[140:141], 0, s[12:13]
	s_mov_b64 s[12:13], 0x30000
	v_lshl_add_u64 v[138:139], v[138:139], 0, s[12:13]
	v_lshl_add_u64 v[142:143], v[142:143], 0, s[12:13]
	s_mov_b64 s[12:13], 0xc00000
	s_mov_b64 s[14:15], 0x10000
	s_lshl_b32 s21, s1, 12
	s_lshl_b32 s22, s4, 13
	s_mov_b32 s5, 0x18000
	v_mov_b32_e32 v0, 0
	v_mov_b32_e32 v1, v0
	v_mov_b32_e32 v2, v0
	v_mov_b32_e32 v3, v0
	v_mov_b32_e32 v4, v0
	v_mov_b32_e32 v5, v0
	v_mov_b32_e32 v6, v0
	v_mov_b32_e32 v7, v0
	v_mov_b32_e32 v8, v0
	v_mov_b32_e32 v9, v0
	v_mov_b32_e32 v10, v0
	v_mov_b32_e32 v11, v0
	v_mov_b32_e32 v12, v0
	v_mov_b32_e32 v13, v0
	v_mov_b32_e32 v14, v0
	v_mov_b32_e32 v15, v0
	v_mov_b32_e32 v16, v0
	v_mov_b32_e32 v17, v0
	v_mov_b32_e32 v18, v0
	v_mov_b32_e32 v19, v0
	v_mov_b32_e32 v20, v0
	v_mov_b32_e32 v21, v0
	v_mov_b32_e32 v22, v0
	v_mov_b32_e32 v23, v0
	v_mov_b32_e32 v24, v0
	v_mov_b32_e32 v25, v0
	v_mov_b32_e32 v26, v0
	v_mov_b32_e32 v27, v0
	v_mov_b32_e32 v28, v0
	v_mov_b32_e32 v29, v0
	v_mov_b32_e32 v30, v0
	v_mov_b32_e32 v31, v0
	v_mov_b32_e32 v32, v0
	v_mov_b32_e32 v33, v0
	v_mov_b32_e32 v34, v0
	v_mov_b32_e32 v35, v0
	v_mov_b32_e32 v36, v0
	v_mov_b32_e32 v37, v0
	v_mov_b32_e32 v38, v0
	v_mov_b32_e32 v39, v0
	v_mov_b32_e32 v40, v0
	v_mov_b32_e32 v41, v0
	v_mov_b32_e32 v42, v0
	v_mov_b32_e32 v43, v0
	v_mov_b32_e32 v44, v0
	v_mov_b32_e32 v45, v0
	v_mov_b32_e32 v46, v0
	v_mov_b32_e32 v47, v0
	v_mov_b32_e32 v48, v0
	v_mov_b32_e32 v49, v0
	v_mov_b32_e32 v50, v0
	v_mov_b32_e32 v51, v0
	v_mov_b32_e32 v52, v0
	v_mov_b32_e32 v53, v0
	v_mov_b32_e32 v54, v0
	v_mov_b32_e32 v55, v0
	v_mov_b32_e32 v56, v0
	v_mov_b32_e32 v57, v0
	v_mov_b32_e32 v58, v0
	v_mov_b32_e32 v59, v0
	v_mov_b32_e32 v60, v0
	v_mov_b32_e32 v61, v0
	v_mov_b32_e32 v62, v0
	v_mov_b32_e32 v63, v0
	v_mov_b32_e32 v64, v0
	v_mov_b32_e32 v65, v0
	v_mov_b32_e32 v66, v0
	v_mov_b32_e32 v67, v0
	v_mov_b32_e32 v68, v0
	v_mov_b32_e32 v69, v0
	v_mov_b32_e32 v70, v0
	v_mov_b32_e32 v71, v0
	v_mov_b32_e32 v72, v0
	v_mov_b32_e32 v73, v0
	v_mov_b32_e32 v74, v0
	v_mov_b32_e32 v75, v0
	v_mov_b32_e32 v76, v0
	v_mov_b32_e32 v77, v0
	v_mov_b32_e32 v78, v0
	v_mov_b32_e32 v79, v0
	v_mov_b32_e32 v80, v0
	v_mov_b32_e32 v81, v0
	v_mov_b32_e32 v82, v0
	v_mov_b32_e32 v83, v0
	v_mov_b32_e32 v84, v0
	v_mov_b32_e32 v85, v0
	v_mov_b32_e32 v86, v0
	v_mov_b32_e32 v87, v0
	v_mov_b32_e32 v88, v0
	v_mov_b32_e32 v89, v0
	v_mov_b32_e32 v90, v0
	v_mov_b32_e32 v91, v0
	v_mov_b32_e32 v92, v0
	v_mov_b32_e32 v93, v0
	v_mov_b32_e32 v94, v0
	v_mov_b32_e32 v95, v0
	v_mov_b32_e32 v96, v0
	v_mov_b32_e32 v97, v0
	v_mov_b32_e32 v98, v0
	v_mov_b32_e32 v99, v0
	v_mov_b32_e32 v100, v0
	v_mov_b32_e32 v101, v0
	v_mov_b32_e32 v102, v0
	v_mov_b32_e32 v103, v0
	v_mov_b32_e32 v104, v0
	v_mov_b32_e32 v105, v0
	v_mov_b32_e32 v106, v0
	v_mov_b32_e32 v107, v0
	v_mov_b32_e32 v108, v0
	v_mov_b32_e32 v109, v0
	v_mov_b32_e32 v110, v0
	v_mov_b32_e32 v111, v0
	v_mov_b32_e32 v112, v0
	v_mov_b32_e32 v113, v0
	v_mov_b32_e32 v114, v0
	v_mov_b32_e32 v115, v0
	v_mov_b32_e32 v116, v0
	v_mov_b32_e32 v117, v0
	v_mov_b32_e32 v118, v0
	v_mov_b32_e32 v119, v0
	v_mov_b32_e32 v120, v0
	v_mov_b32_e32 v121, v0
	v_mov_b32_e32 v122, v0
	v_mov_b32_e32 v123, v0
	v_mov_b32_e32 v124, v0
	v_mov_b32_e32 v125, v0
	v_mov_b32_e32 v126, v0
	v_mov_b32_e32 v127, v0
	s_waitcnt vmcnt(8)
	s_barrier
	s_add_i32 s7, s5, 0xfffe8000
	s_and_b32 s7, s7, 0x18000
	s_add_i32 s8, s7, s21
	s_or_b32 s7, s7, s22
	v_add_u32_e32 v252, s8, v189
	v_add_u32_e32 v253, s7, v189
	ds_read_b128 v[154:157], v252
	ds_read_b128 v[162:165], v253 offset:16384
	ds_read_b128 v[158:161], v252 offset:2048
	ds_read_b128 v[166:169], v253 offset:18432
	ds_read_b128 v[170:173], v253 offset:20480
	ds_read_b128 v[174:177], v253 offset:22528
	.p2align 6
; #define WAIT_V(n) asm volatile("s_waitcnt vmcnt(%0)" ::"n"(n) : "memory")
; #define RAW_BARRIER() do { asm volatile("s_waitcnt lgkmcnt(0)" ::: "memory"); __builtin_amdgcn_s_barrier(); } while (0)
; template <typename FA, typename FB, typename FE>
; DI void gemm_tile(char* lds, int K, int astride, int bstride, FA arow, FB brow, FE epi) {
;     ...
;   for (int kt = 0; kt < nk; ++kt) {
;     if (kt + 2 < nk) WAIT_V(8); else if (kt + 1 < nk) WAIT_V(4); else WAIT_V(0);
;     RAW_BARRIER();
;     if (kt + 3 < nk) stage((kt + 3) & 3, kt + 3);
.Lgf_P8_loop:
	s_and_b32 s6, s5, 0x18000
	s_add_i32 s6, s17, s6
	s_cmp_lt_u32 s5, 0x80000
	s_cselect_b64 s[10:11], -1, 0
	s_cmp_ge_u32 s5, 0x88000
	s_cbranch_scc1 .Lgf_P8_w0
	s_waitcnt vmcnt(4)
	s_branch .Lgf_P8_wd

; #define MFMA(a, b, c) __builtin_amdgcn_mfma_f32_32x32x16_bf16((a), (b), (c), 0, 0, 0)
; DI unsigned pk2(float a, float b) { fl2_t f = {a, b}; bf2_t r = __builtin_convertvector(f, bf2_t); return __builtin_bit_cast(unsigned, r); }
; #define WAIT_V(n) asm volatile("s_waitcnt vmcnt(%0)" ::"n"(n) : "memory")
; #define RAW_BARRIER() do { asm volatile("s_waitcnt lgkmcnt(0)" ::: "memory"); __builtin_amdgcn_s_barrier(); } while (0)
; template <typename FA, typename FB, typename FE>
; DI void gemm_tile(char* lds, int K, int astride, int bstride, FA arow, FB brow, FE epi) {
;     ...
;   for (int kt = 0; kt < nk; ++kt) {
;     if (kt + 2 < nk) WAIT_V(8); else if (kt + 1 < nk) WAIT_V(4); else WAIT_V(0);
;     RAW_BARRIER();
;     if (kt + 3 < nk) stage((kt + 3) & 3, kt + 3);
;     const char* sa = lds + (kt & 3) * 32768 + wm * 4096;
;     const char* sb = lds + (kt & 3) * 32768 + 16384 + wn * 8192;
; #pragma unroll
;     for (int ks = 0; ks < 2; ++ks) {
;       bf16x8 a0 = *(const bf16x8*)(sa + foff[ks]), a1 = *(const bf16x8*)(sa + 2048 + foff[ks]);
; #pragma unroll
;       for (int nt = 0; nt < 4; ++nt) {
;         bf16x8 bb = *(const bf16x8*)(sb + nt * 2048 + foff[ks]);
;         acc[0][nt] = MFMA(a0, bb, acc[0][nt]);
;         acc[1][nt] = MFMA(a1, bb, acc[1][nt]);
;       }
;     }
;   }
;   RAW_BARRIER();
;   bfr* Cs = (bfr*)lds;
; #pragma unroll
;   for (int mt = 0; mt < 2; ++mt)
; #pragma unroll
;     for (int nt = 0; nt < 4; ++nt)
; #pragma unroll
;       for (int i = 0; i < 16; i += 2) {
;         const int row = wm * 64 + mt * 32 + (i & 3) + 8 * (i >> 2) + 4 * h8;
;         const unsigned pr = pk2(acc[mt][nt][i], acc[mt][nt][i + 1]);
;         Cs[row * CSS + wn * 128 + nt * 32 + r] = (bfr)(pr & 0xffffu);
;         Cs[(row + 1) * CSS + wn * 128 + nt * 32 + r] = (bfr)(pr >> 16);
;       }
.Lgf_P8_wd:
	s_mov_b32 m0, s6
	s_barrier
	s_add_i32 s7, s5, 0xfffe8000
	s_and_b32 s7, s7, 0x18000
	s_add_i32 s8, s7, s21
	s_or_b32 s7, s7, s22
	v_add_u32_e32 v254, s8, v190
	v_add_u32_e32 v255, s7, v190
	s_waitcnt lgkmcnt(4)
	v_mfma_f32_32x32x16_bf16 v[112:127], v[154:157], v[162:165], v[112:127]
	s_mov_b64 exec, s[10:11]
	global_load_lds_dwordx4 v[136:137], off
	s_mov_b64 exec, -1
	s_add_i32 m0, s6, 0x4000
	ds_read_b128 v[178:181], v254
	s_waitcnt lgkmcnt(4)
	v_mfma_f32_32x32x16_bf16 v[48:63], v[158:161], v[162:165], v[48:63]
	s_mov_b64 exec, s[10:11]
	global_load_lds_dwordx4 v[138:139], off
	s_mov_b64 exec, -1
	s_add_i32 m0, s6, 0x400
	ds_read_b128 v[232:235], v255 offset:16384
	s_waitcnt lgkmcnt(4)
	v_mfma_f32_32x32x16_bf16 v[96:111], v[154:157], v[166:169], v[96:111]
	s_mov_b64 exec, s[10:11]
	global_load_lds_dwordx4 v[140:141], off
	s_mov_b64 exec, -1
	s_add_i32 m0, s6, 0x4400
	ds_read_b128 v[182:185], v254 offset:2048
	v_mfma_f32_32x32x16_bf16 v[32:47], v[158:161], v[166:169], v[32:47]
	ds_read_b128 v[236:239], v255 offset:18432
	s_mov_b64 exec, s[10:11]
	global_load_lds_dwordx4 v[142:143], off
	s_mov_b64 exec, -1
	s_waitcnt lgkmcnt(5)
	v_mfma_f32_32x32x16_bf16 v[80:95], v[154:157], v[170:173], v[80:95]
	ds_read_b128 v[240:243], v255 offset:20480
	v_lshl_add_u64 v[138:139], v[138:139], 0, s[14:15]
	v_lshl_add_u64 v[142:143], v[142:143], 0, s[14:15]
	v_mfma_f32_32x32x16_bf16 v[16:31], v[158:161], v[170:173], v[16:31]
	ds_read_b128 v[248:251], v255 offset:22528
	v_lshl_add_u64 v[136:137], v[136:137], 0, s[12:13]
	v_lshl_add_u64 v[140:141], v[140:141], 0, s[12:13]
	s_waitcnt lgkmcnt(6)
	v_mfma_f32_32x32x16_bf16 v[64:79], v[154:157], v[174:177], v[64:79]
	s_add_i32 s7, s5, 0xffff0000
	s_and_b32 s7, s7, 0x18000
	s_add_i32 s8, s7, s21
	s_or_b32 s7, s7, s22
	v_mfma_f32_32x32x16_bf16 v[0:15], v[158:161], v[174:177], v[0:15]
	v_add_u32_e32 v252, s8, v189
	v_add_u32_e32 v253, s7, v189
	s_waitcnt lgkmcnt(4)
	v_mfma_f32_32x32x16_bf16 v[112:127], v[178:181], v[232:235], v[112:127]
	ds_read_b128 v[154:157], v252
	s_waitcnt lgkmcnt(4)
	v_mfma_f32_32x32x16_bf16 v[48:63], v[182:185], v[232:235], v[48:63]
	ds_read_b128 v[162:165], v253 offset:16384
	s_waitcnt lgkmcnt(4)
	v_mfma_f32_32x32x16_bf16 v[96:111], v[178:181], v[236:239], v[96:111]
	ds_read_b128 v[158:161], v252 offset:2048
	v_mfma_f32_32x32x16_bf16 v[32:47], v[182:185], v[236:239], v[32:47]
	ds_read_b128 v[166:169], v253 offset:18432
	s_waitcnt lgkmcnt(5)
	v_mfma_f32_32x32x16_bf16 v[80:95], v[178:181], v[240:243], v[80:95]
	ds_read_b128 v[170:173], v253 offset:20480
	v_mfma_f32_32x32x16_bf16 v[16:31], v[182:185], v[240:243], v[16:31]
	ds_read_b128 v[174:177], v253 offset:22528
	s_waitcnt lgkmcnt(6)
	v_mfma_f32_32x32x16_bf16 v[64:79], v[178:181], v[248:251], v[64:79]
	s_add_i32 s5, s5, 0x8000
	v_mfma_f32_32x32x16_bf16 v[0:15], v[182:185], v[248:251], v[0:15]
	s_cmp_eq_u32 s5, 0x98000
	s_cbranch_scc0 .Lgf_P8_loop
	s_waitcnt lgkmcnt(0)
	s_barrier
	s_nop 15
	v_lshl_or_b32 v128, s1, 6, v191
	s_movk_i32 s1, 0x210
	s_nop 10
	v_cvt_pk_bf16_f32 v96, v96, v97
	v_cvt_pk_bf16_f32 v136, v112, v113
	v_lshl_or_b32 v112, s4, 8, v216
	v_mad_u64_u32 v[112:113], s[4:5], v128, s1, v[112:113]
	v_cvt_pk_bf16_f32 v113, v114, v115
	ds_write_b16 v112, v136
	ds_write_b16_d16_hi v112, v136 offset:528
	ds_write_b16 v112, v113 offset:1056
	ds_write_b16_d16_hi v112, v113 offset:1584
	v_cvt_pk_bf16_f32 v113, v116, v117
	ds_write_b16 v112, v113 offset:4224
	ds_write_b16_d16_hi v112, v113 offset:4752
	v_cvt_pk_bf16_f32 v113, v118, v119
	ds_write_b16 v112, v113 offset:5280
	ds_write_b16_d16_hi v112, v113 offset:5808
	v_cvt_pk_bf16_f32 v113, v120, v121
	ds_write_b16 v112, v113 offset:8448
	ds_write_b16_d16_hi v112, v113 offset:8976
	v_cvt_pk_bf16_f32 v113, v122, v123
	ds_write_b16 v112, v113 offset:9504
	ds_write_b16_d16_hi v112, v113 offset:10032
	v_cvt_pk_bf16_f32 v113, v124, v125
	ds_write_b16 v112, v113 offset:12672
	ds_write_b16_d16_hi v112, v113 offset:13200
	v_cvt_pk_bf16_f32 v113, v126, v127
	ds_write_b16 v112, v113 offset:13728
	ds_write_b16_d16_hi v112, v113 offset:14256
	ds_write_b16 v112, v96 offset:64
	ds_write_b16_d16_hi v112, v96 offset:592
	v_cvt_pk_bf16_f32 v96, v98, v99
	ds_write_b16 v112, v96 offset:1120
	ds_write_b16_d16_hi v112, v96 offset:1648
	v_cvt_pk_bf16_f32 v96, v100, v101
	ds_write_b16 v112, v96 offset:4288
	ds_write_b16_d16_hi v112, v96 offset:4816
	v_cvt_pk_bf16_f32 v96, v102, v103
	ds_write_b16 v112, v96 offset:5344
	ds_write_b16_d16_hi v112, v96 offset:5872
	v_cvt_pk_bf16_f32 v96, v104, v105
	ds_write_b16 v112, v96 offset:8512
	ds_write_b16_d16_hi v112, v96 offset:9040
	v_cvt_pk_bf16_f32 v96, v106, v107
	ds_write_b16 v112, v96 offset:9568
	ds_write_b16_d16_hi v112, v96 offset:10096
	v_cvt_pk_bf16_f32 v96, v108, v109
	ds_write_b16 v112, v96 offset:12736
	ds_write_b16_d16_hi v112, v96 offset:13264
	v_cvt_pk_bf16_f32 v96, v110, v111
	v_cvt_pk_bf16_f32 v80, v80, v81
	ds_write_b16 v112, v96 offset:13792
	ds_write_b16_d16_hi v112, v96 offset:14320
	ds_write_b16 v112, v80 offset:128
	ds_write_b16_d16_hi v112, v80 offset:656
	v_cvt_pk_bf16_f32 v80, v82, v83
	ds_write_b16 v112, v80 offset:1184
	ds_write_b16_d16_hi v112, v80 offset:1712
	v_cvt_pk_bf16_f32 v80, v84, v85
	ds_write_b16 v112, v80 offset:4352
	ds_write_b16_d16_hi v112, v80 offset:4880
	v_cvt_pk_bf16_f32 v80, v86, v87
	ds_write_b16 v112, v80 offset:5408
	ds_write_b16_d16_hi v112, v80 offset:5936
	v_cvt_pk_bf16_f32 v80, v88, v89
	ds_write_b16 v112, v80 offset:8576
	ds_write_b16_d16_hi v112, v80 offset:9104
	v_cvt_pk_bf16_f32 v80, v90, v91
	ds_write_b16 v112, v80 offset:9632
	ds_write_b16_d16_hi v112, v80 offset:10160
	v_cvt_pk_bf16_f32 v80, v92, v93
; DI unsigned pk2(float a, float b) { fl2_t f = {a, b}; bf2_t r = __builtin_convertvector(f, bf2_t); return __builtin_bit_cast(unsigned, r); }
; template <typename FA, typename FB, typename FE>
; DI void gemm_tile(char* lds, int K, int astride, int bstride, FA arow, FB brow, FE epi) {
;     ...
; #pragma unroll
;   for (int mt = 0; mt < 2; ++mt)
; #pragma unroll
;     for (int nt = 0; nt < 4; ++nt)
; #pragma unroll
;       for (int i = 0; i < 16; i += 2) {
;         const int row = wm * 64 + mt * 32 + (i & 3) + 8 * (i >> 2) + 4 * h8;
;         const unsigned pr = pk2(acc[mt][nt][i], acc[mt][nt][i + 1]);
;         Cs[row * CSS + wn * 128 + nt * 32 + r] = (bfr)(pr & 0xffffu);
;         Cs[(row + 1) * CSS + wn * 128 + nt * 32 + r] = (bfr)(pr >> 16);
;       }
;   __syncthreads();
	ds_write_b16 v112, v80 offset:12800
	ds_write_b16_d16_hi v112, v80 offset:13328
	v_cvt_pk_bf16_f32 v80, v94, v95
	v_cvt_pk_bf16_f32 v64, v64, v65
	ds_write_b16 v112, v80 offset:13856
	ds_write_b16_d16_hi v112, v80 offset:14384
	ds_write_b16 v112, v64 offset:192
	ds_write_b16_d16_hi v112, v64 offset:720
	v_cvt_pk_bf16_f32 v64, v66, v67
	ds_write_b16 v112, v64 offset:1248
	ds_write_b16_d16_hi v112, v64 offset:1776
	v_cvt_pk_bf16_f32 v64, v68, v69
	ds_write_b16 v112, v64 offset:4416
	ds_write_b16_d16_hi v112, v64 offset:4944
	v_cvt_pk_bf16_f32 v64, v70, v71
	ds_write_b16 v112, v64 offset:5472
	ds_write_b16_d16_hi v112, v64 offset:6000
	v_cvt_pk_bf16_f32 v64, v72, v73
	ds_write_b16 v112, v64 offset:8640
	ds_write_b16_d16_hi v112, v64 offset:9168
	v_cvt_pk_bf16_f32 v64, v74, v75
	ds_write_b16 v112, v64 offset:9696
	ds_write_b16_d16_hi v112, v64 offset:10224
	v_cvt_pk_bf16_f32 v64, v76, v77
	ds_write_b16 v112, v64 offset:12864
	ds_write_b16_d16_hi v112, v64 offset:13392
	v_cvt_pk_bf16_f32 v64, v78, v79
	v_cvt_pk_bf16_f32 v48, v48, v49
	ds_write_b16 v112, v64 offset:13920
	ds_write_b16_d16_hi v112, v64 offset:14448
	ds_write_b16 v112, v48 offset:16896
	ds_write_b16_d16_hi v112, v48 offset:17424
	v_cvt_pk_bf16_f32 v48, v50, v51
	ds_write_b16 v112, v48 offset:17952
	ds_write_b16_d16_hi v112, v48 offset:18480
	v_cvt_pk_bf16_f32 v48, v52, v53
	ds_write_b16 v112, v48 offset:21120
	ds_write_b16_d16_hi v112, v48 offset:21648
	v_cvt_pk_bf16_f32 v48, v54, v55
	ds_write_b16 v112, v48 offset:22176
	ds_write_b16_d16_hi v112, v48 offset:22704
	v_cvt_pk_bf16_f32 v48, v56, v57
	ds_write_b16 v112, v48 offset:25344
	ds_write_b16_d16_hi v112, v48 offset:25872
	v_cvt_pk_bf16_f32 v48, v58, v59
	ds_write_b16 v112, v48 offset:26400
	ds_write_b16_d16_hi v112, v48 offset:26928
	v_cvt_pk_bf16_f32 v48, v60, v61
	ds_write_b16 v112, v48 offset:29568
	ds_write_b16_d16_hi v112, v48 offset:30096
	v_cvt_pk_bf16_f32 v48, v62, v63
	v_cvt_pk_bf16_f32 v32, v32, v33
	ds_write_b16 v112, v48 offset:30624
	ds_write_b16_d16_hi v112, v48 offset:31152
	ds_write_b16 v112, v32 offset:16960
	ds_write_b16_d16_hi v112, v32 offset:17488
	v_cvt_pk_bf16_f32 v32, v34, v35
	ds_write_b16 v112, v32 offset:18016
	ds_write_b16_d16_hi v112, v32 offset:18544
	v_cvt_pk_bf16_f32 v32, v36, v37
	ds_write_b16 v112, v32 offset:21184
	ds_write_b16_d16_hi v112, v32 offset:21712
	v_cvt_pk_bf16_f32 v32, v38, v39
	ds_write_b16 v112, v32 offset:22240
	ds_write_b16_d16_hi v112, v32 offset:22768
	v_cvt_pk_bf16_f32 v32, v40, v41
	ds_write_b16 v112, v32 offset:25408
	ds_write_b16_d16_hi v112, v32 offset:25936
	v_cvt_pk_bf16_f32 v32, v42, v43
	ds_write_b16 v112, v32 offset:26464
	ds_write_b16_d16_hi v112, v32 offset:26992
	v_cvt_pk_bf16_f32 v32, v44, v45
	ds_write_b16 v112, v32 offset:29632
	ds_write_b16_d16_hi v112, v32 offset:30160
	v_cvt_pk_bf16_f32 v32, v46, v47
	v_cvt_pk_bf16_f32 v16, v16, v17
	ds_write_b16 v112, v32 offset:30688
	ds_write_b16_d16_hi v112, v32 offset:31216
	ds_write_b16 v112, v16 offset:17024
	ds_write_b16_d16_hi v112, v16 offset:17552
	v_cvt_pk_bf16_f32 v16, v18, v19
	ds_write_b16 v112, v16 offset:18080
	ds_write_b16_d16_hi v112, v16 offset:18608
	v_cvt_pk_bf16_f32 v16, v20, v21
	ds_write_b16 v112, v16 offset:21248
	ds_write_b16_d16_hi v112, v16 offset:21776
	v_cvt_pk_bf16_f32 v16, v22, v23
	ds_write_b16 v112, v16 offset:22304
	ds_write_b16_d16_hi v112, v16 offset:22832
	v_cvt_pk_bf16_f32 v16, v24, v25
	ds_write_b16 v112, v16 offset:25472
	ds_write_b16_d16_hi v112, v16 offset:26000
	v_cvt_pk_bf16_f32 v16, v26, v27
	ds_write_b16 v112, v16 offset:26528
	ds_write_b16_d16_hi v112, v16 offset:27056
	v_cvt_pk_bf16_f32 v16, v28, v29
	ds_write_b16 v112, v16 offset:29696
	ds_write_b16_d16_hi v112, v16 offset:30224
	v_cvt_pk_bf16_f32 v16, v30, v31
	v_cvt_pk_bf16_f32 v0, v0, v1
	ds_write_b16 v112, v16 offset:30752
	ds_write_b16_d16_hi v112, v16 offset:31280
	ds_write_b16 v112, v0 offset:17088
	ds_write_b16_d16_hi v112, v0 offset:17616
	v_cvt_pk_bf16_f32 v0, v2, v3
	ds_write_b16 v112, v0 offset:18144
	ds_write_b16_d16_hi v112, v0 offset:18672
	v_cvt_pk_bf16_f32 v0, v4, v5
	ds_write_b16 v112, v0 offset:21312
	ds_write_b16_d16_hi v112, v0 offset:21840
	v_cvt_pk_bf16_f32 v0, v6, v7
	ds_write_b16 v112, v0 offset:22368
	ds_write_b16_d16_hi v112, v0 offset:22896
	v_cvt_pk_bf16_f32 v0, v8, v9
	ds_write_b16 v112, v0 offset:25536
	ds_write_b16_d16_hi v112, v0 offset:26064
	v_cvt_pk_bf16_f32 v0, v10, v11
	ds_write_b16 v112, v0 offset:26592
	ds_write_b16_d16_hi v112, v0 offset:27120
	v_cvt_pk_bf16_f32 v0, v12, v13
	ds_write_b16 v112, v0 offset:29760
	ds_write_b16_d16_hi v112, v0 offset:30288
	v_cvt_pk_bf16_f32 v0, v14, v15
	ds_write_b16 v112, v0 offset:30816
	ds_write_b16_d16_hi v112, v0 offset:31344
	s_waitcnt vmcnt(0) lgkmcnt(0)
	s_barrier
; DI void phase_moe(const Params& p, char* lds, int mode) {
;     ...
;           float4 ov[16]; u32x2 yv[16]; float gt[16]; int tk[16];
; #pragma unroll
;           for (int ps = 0; ps < 16; ++ps) {
;             const int grow = half * 128 + ps * 8 + (tid >> 5);
;             tk[ps] = rowtok[grow];
;             gt[ps] = gate[(size_t)k * T + tk[ps]];
;             ov[ps] = *(const float4*)(p.out + (size_t)tk[ps] * D + col);
;             yv[ps] = *(const u32x2*)(Y0 + (size_t)tk[ps] * D + col);
;           }
	ds_read2_b32 v[168:169], v194 offset1:8
	v_or_b32_e32 v64, s0, v192
	v_ashrrev_i32_e32 v65, 31, v64
	v_lshl_add_u64 v[72:73], v[64:65], 1, s[42:43]
	ds_read2_b32 v[154:155], v194 offset0:16 offset1:24
	s_waitcnt lgkmcnt(1)
	v_ashrrev_i32_e32 v1, 31, v168
	v_mov_b32_e32 v0, v168
	v_lshl_add_u64 v[2:3], v[0:1], 2, s[44:45]
	v_lshlrev_b64 v[184:185], 12, v[0:1]
	v_lshlrev_b64 v[0:1], 11, v[0:1]
	v_lshl_add_u64 v[66:67], v[64:65], 2, s[46:47]
	v_lshl_add_u64 v[0:1], v[72:73], 0, v[0:1]
	global_load_dword v180, v[2:3], off
	v_lshl_add_u64 v[2:3], v[66:67], 0, v[184:185]
	global_load_dwordx2 v[182:183], v[0:1], off
	v_ashrrev_i32_e32 v1, 31, v169
	v_mov_b32_e32 v0, v169
	global_load_dwordx4 v[60:63], v[2:3], off
	v_lshl_add_u64 v[2:3], v[0:1], 2, s[44:45]
	v_lshlrev_b64 v[178:179], 12, v[0:1]
	v_lshlrev_b64 v[0:1], 11, v[0:1]
	v_lshl_add_u64 v[0:1], v[72:73], 0, v[0:1]
	global_load_dword v172, v[2:3], off
	v_lshl_add_u64 v[2:3], v[66:67], 0, v[178:179]
	global_load_dwordx2 v[174:175], v[0:1], off
	s_waitcnt lgkmcnt(0)
	v_ashrrev_i32_e32 v1, 31, v154
	v_mov_b32_e32 v0, v154
	global_load_dwordx4 v[56:59], v[2:3], off
	v_lshl_add_u64 v[2:3], v[0:1], 2, s[44:45]
	v_lshlrev_b64 v[176:177], 12, v[0:1]
	v_lshlrev_b64 v[0:1], 11, v[0:1]
	ds_read2_b32 v[140:141], v194 offset0:32 offset1:40
	v_lshl_add_u64 v[0:1], v[72:73], 0, v[0:1]
	global_load_dword v166, v[2:3], off
	v_lshl_add_u64 v[2:3], v[66:67], 0, v[176:177]
	global_load_dwordx2 v[170:171], v[0:1], off
	v_ashrrev_i32_e32 v1, 31, v155
	v_mov_b32_e32 v0, v155
	global_load_dwordx4 v[52:55], v[2:3], off
	v_lshl_add_u64 v[2:3], v[0:1], 2, s[44:45]
	v_lshlrev_b64 v[164:165], 12, v[0:1]
	v_lshlrev_b64 v[0:1], 11, v[0:1]
	v_lshl_add_u64 v[0:1], v[72:73], 0, v[0:1]
	global_load_dword v158, v[2:3], off
	v_lshl_add_u64 v[2:3], v[66:67], 0, v[164:165]
	global_load_dwordx2 v[160:161], v[0:1], off
	s_waitcnt lgkmcnt(0)
	v_ashrrev_i32_e32 v1, 31, v140
	v_mov_b32_e32 v0, v140
	global_load_dwordx4 v[48:51], v[2:3], off
	v_lshl_add_u64 v[2:3], v[0:1], 2, s[44:45]
	v_lshlrev_b64 v[162:163], 12, v[0:1]
	v_lshlrev_b64 v[0:1], 11, v[0:1]
	ds_read2_b32 v[120:121], v194 offset0:48 offset1:56
	v_lshl_add_u64 v[0:1], v[72:73], 0, v[0:1]
	global_load_dword v152, v[2:3], off
	v_lshl_add_u64 v[2:3], v[66:67], 0, v[162:163]
	global_load_dwordx2 v[156:157], v[0:1], off
	v_ashrrev_i32_e32 v1, 31, v141
	v_mov_b32_e32 v0, v141
	global_load_dwordx4 v[44:47], v[2:3], off
	v_lshl_add_u64 v[2:3], v[0:1], 2, s[44:45]
	v_lshlrev_b64 v[150:151], 12, v[0:1]
	v_lshlrev_b64 v[0:1], 11, v[0:1]
	v_lshl_add_u64 v[0:1], v[72:73], 0, v[0:1]
	global_load_dword v144, v[2:3], off
	v_lshl_add_u64 v[2:3], v[66:67], 0, v[150:151]
	global_load_dwordx2 v[146:147], v[0:1], off
	s_waitcnt lgkmcnt(0)
	v_ashrrev_i32_e32 v1, 31, v120
	v_mov_b32_e32 v0, v120
	global_load_dwordx4 v[40:43], v[2:3], off
	v_lshl_add_u64 v[2:3], v[0:1], 2, s[44:45]
	v_lshlrev_b64 v[148:149], 12, v[0:1]
	v_lshlrev_b64 v[0:1], 11, v[0:1]
	ds_read2_b32 v[106:107], v194 offset0:64 offset1:72
	v_lshl_add_u64 v[0:1], v[72:73], 0, v[0:1]
	global_load_dword v128, v[2:3], off
	v_lshl_add_u64 v[2:3], v[66:67], 0, v[148:149]
	global_load_dwordx2 v[142:143], v[0:1], off
	v_ashrrev_i32_e32 v1, 31, v121
	v_mov_b32_e32 v0, v121
	global_load_dwordx4 v[36:39], v[2:3], off
	v_lshl_add_u64 v[2:3], v[0:1], 2, s[44:45]
	v_lshlrev_b64 v[138:139], 12, v[0:1]
	v_lshlrev_b64 v[0:1], 11, v[0:1]
	v_lshl_add_u64 v[0:1], v[72:73], 0, v[0:1]
	global_load_dword v124, v[2:3], off
	v_lshl_add_u64 v[2:3], v[66:67], 0, v[138:139]
	global_load_dwordx2 v[126:127], v[0:1], off
	s_waitcnt lgkmcnt(0)
	v_ashrrev_i32_e32 v1, 31, v106
	v_mov_b32_e32 v0, v106
	global_load_dwordx4 v[32:35], v[2:3], off
	v_lshl_add_u64 v[2:3], v[0:1], 2, s[44:45]
	v_lshlrev_b64 v[136:137], 12, v[0:1]
	v_lshlrev_b64 v[0:1], 11, v[0:1]
	ds_read2_b32 v[92:93], v194 offset0:80 offset1:88
	v_lshl_add_u64 v[0:1], v[72:73], 0, v[0:1]
	global_load_dword v118, v[2:3], off
	v_lshl_add_u64 v[2:3], v[66:67], 0, v[136:137]
	global_load_dwordx2 v[122:123], v[0:1], off
	v_ashrrev_i32_e32 v1, 31, v107
	v_mov_b32_e32 v0, v107
	global_load_dwordx4 v[28:31], v[2:3], off
	v_lshl_add_u64 v[2:3], v[0:1], 2, s[44:45]
	v_lshlrev_b64 v[116:117], 12, v[0:1]
	v_lshlrev_b64 v[0:1], 11, v[0:1]
	v_lshl_add_u64 v[0:1], v[72:73], 0, v[0:1]
	global_load_dword v110, v[2:3], off
	v_lshl_add_u64 v[2:3], v[66:67], 0, v[116:117]
	global_load_dwordx2 v[112:113], v[0:1], off
	s_waitcnt lgkmcnt(0)
; DI void phase_moe(const Params& p, char* lds, int mode) {
;     ...
;           for (int ps = 0; ps < 16; ++ps) {
;             const int grow = half * 128 + ps * 8 + (tid >> 5);
;             tk[ps] = rowtok[grow];
;             gt[ps] = gate[(size_t)k * T + tk[ps]];
;             ov[ps] = *(const float4*)(p.out + (size_t)tk[ps] * D + col);
;             yv[ps] = *(const u32x2*)(Y0 + (size_t)tk[ps] * D + col);
;           }
;           asm volatile("" ::: "memory");
; #pragma unroll
;           for (int ps = 0; ps < 16; ++ps) {
;             const int row = ps * 8 + (tid >> 5);
;             if (r0 + half * 128 + row < n) {
;               int br, s_, S_; tok_info(tk[ps], br, s_, S_);
;               const float4 g2 = *(const float4*)(g2t + br * 256 + ch * 128 + c4);
;               float4 c = cs4(Cs, row, c4);
;               float4 o = ov[ps];
;               const float g = gt[ps];
;               o.x += g2.x * (__uint_as_float(yv[ps][0] << 16) + g * c.x);
;               o.y += g2.y * (__uint_as_float(yv[ps][0] & 0xffff0000u) + g * c.y);
;               o.z += g2.z * (__uint_as_float(yv[ps][1] << 16) + g * c.z);
;               o.w += g2.w * (__uint_as_float(yv[ps][1] & 0xffff0000u) + g * c.w);
;               *(float4*)(p.out + (size_t)tk[ps] * D + col) = o;
	v_ashrrev_i32_e32 v1, 31, v92
	v_mov_b32_e32 v0, v92
	global_load_dwordx4 v[24:27], v[2:3], off
	v_lshl_add_u64 v[2:3], v[0:1], 2, s[44:45]
	v_lshlrev_b64 v[114:115], 12, v[0:1]
	v_lshlrev_b64 v[0:1], 11, v[0:1]
	ds_read2_b32 v[78:79], v194 offset0:96 offset1:104
	v_lshl_add_u64 v[0:1], v[72:73], 0, v[0:1]
	global_load_dword v104, v[2:3], off
	v_lshl_add_u64 v[2:3], v[66:67], 0, v[114:115]
	global_load_dwordx2 v[108:109], v[0:1], off
	v_ashrrev_i32_e32 v1, 31, v93
	v_mov_b32_e32 v0, v93
	global_load_dwordx4 v[20:23], v[2:3], off
	v_lshl_add_u64 v[2:3], v[0:1], 2, s[44:45]
	v_lshlrev_b64 v[102:103], 12, v[0:1]
	v_lshlrev_b64 v[0:1], 11, v[0:1]
	v_lshl_add_u64 v[0:1], v[72:73], 0, v[0:1]
	global_load_dword v96, v[2:3], off
	v_lshl_add_u64 v[2:3], v[66:67], 0, v[102:103]
	global_load_dwordx2 v[98:99], v[0:1], off
	s_waitcnt lgkmcnt(0)
	v_ashrrev_i32_e32 v1, 31, v78
	v_mov_b32_e32 v0, v78
	global_load_dwordx4 v[16:19], v[2:3], off
	v_lshl_add_u64 v[2:3], v[0:1], 2, s[44:45]
	v_lshlrev_b64 v[100:101], 12, v[0:1]
	v_lshlrev_b64 v[0:1], 11, v[0:1]
	ds_read2_b32 v[68:69], v194 offset0:112 offset1:120
	v_lshl_add_u64 v[0:1], v[72:73], 0, v[0:1]
	global_load_dword v90, v[2:3], off
	v_lshl_add_u64 v[2:3], v[66:67], 0, v[100:101]
	global_load_dwordx2 v[94:95], v[0:1], off
	v_ashrrev_i32_e32 v1, 31, v79
	v_mov_b32_e32 v0, v79
	global_load_dwordx4 v[12:15], v[2:3], off
	v_lshl_add_u64 v[2:3], v[0:1], 2, s[44:45]
	v_lshlrev_b64 v[88:89], 12, v[0:1]
	v_lshlrev_b64 v[0:1], 11, v[0:1]
	v_lshl_add_u64 v[0:1], v[72:73], 0, v[0:1]
	global_load_dword v82, v[2:3], off
	v_lshl_add_u64 v[2:3], v[66:67], 0, v[88:89]
	global_load_dwordx2 v[84:85], v[0:1], off
	s_waitcnt lgkmcnt(0)
	v_ashrrev_i32_e32 v1, 31, v68
	v_mov_b32_e32 v0, v68
	global_load_dwordx4 v[8:11], v[2:3], off
	v_lshl_add_u64 v[2:3], v[0:1], 2, s[44:45]
	v_lshlrev_b64 v[86:87], 12, v[0:1]
	v_lshlrev_b64 v[0:1], 11, v[0:1]
	v_lshl_add_u64 v[0:1], v[72:73], 0, v[0:1]
	v_ashrrev_i32_e32 v221, 31, v69
	v_mov_b32_e32 v220, v69
	global_load_dwordx2 v[80:81], v[0:1], off
	v_lshl_add_u64 v[0:1], v[220:221], 2, s[44:45]
	v_lshlrev_b64 v[74:75], 12, v[220:221]
	v_lshlrev_b64 v[220:221], 11, v[220:221]
	global_load_dword v76, v[2:3], off
	v_lshl_add_u64 v[2:3], v[66:67], 0, v[86:87]
	global_load_dword v70, v[0:1], off
	v_lshl_add_u64 v[0:1], v[66:67], 0, v[74:75]
	v_lshl_add_u64 v[72:73], v[72:73], 0, v[220:221]
	global_load_dwordx4 v[4:7], v[2:3], off
	v_add_u32_e32 v71, v153, v193
	global_load_dwordx4 v[0:3], v[0:1], off
	v_cmp_lt_i32_e32 vcc, v71, v145
	global_load_dwordx2 v[72:73], v[72:73], off
	s_and_saveexec_b64 s[4:5], vcc
	s_cbranch_execz .LBB0_430
	v_add_u32_e32 v71, 0xffff0000, v168
	v_lshrrev_b32_e32 v71, 14, v71
	v_add_u32_e32 v71, 16, v71
	v_ashrrev_i32_e32 v77, 12, v168
	v_cmp_gt_i32_e64 s[0:1], s33, v168
	ds_read_b64 v[224:225], v196
	s_waitcnt vmcnt(46)
	v_lshlrev_b32_e32 v228, 16, v182
	v_cndmask_b32_e64 v71, v71, v77, s[0:1]
	v_lshl_add_u32 v71, v71, 10, v195
	ds_read_b128 v[220:223], v71
	s_waitcnt lgkmcnt(1)
	v_lshlrev_b32_e32 v226, 16, v224
	v_and_b32_e32 v227, 0xffff0000, v224
	v_and_b32_e32 v229, 0xffff0000, v182
	v_pk_fma_f32 v[226:227], v[180:181], v[226:227], v[228:229] op_sel_hi:[0,1,1]
	s_waitcnt vmcnt(45) lgkmcnt(0)
	v_pk_fma_f32 v[60:61], v[220:221], v[226:227], v[60:61]
	v_lshlrev_b32_e32 v220, 16, v225
	v_and_b32_e32 v221, 0xffff0000, v225
	v_lshlrev_b32_e32 v182, 16, v183
	v_and_b32_e32 v183, 0xffff0000, v183
	v_lshl_add_u64 v[184:185], s[46:47], 0, v[184:185]
	v_pk_fma_f32 v[180:181], v[180:181], v[220:221], v[182:183] op_sel_hi:[0,1,1]
	v_lshl_add_u64 v[184:185], v[64:65], 2, v[184:185]
	v_pk_fma_f32 v[62:63], v[222:223], v[180:181], v[62:63]
	global_store_dwordx4 v[184:185], v[60:63], off
